# HGRN input-projection epilogue: second half's bound-logit loads issued with the first half's; mid-epilogue wait no longer drains the output stores
# baseline (speedup 1.0000x reference)
; __device__ __forceinline__ float sigmoidf_(float a) { return __builtin_amdgcn_rcpf(1.f + __expf(-a)); }
;   __device__ __forceinline__ void operator()(const Acc& acc, int brow, int bcol, int wr, int wc, int fr, int fq, int nai) const {
;     ...
;       for (int bj = 0; bj < 2; ++bj) {
;         const int c = cb + 128 * bj;
;         f32x4 lb[2];
; #pragma unroll
;         for (int n = 0; n < 2; ++n) {
;           const f32x4 z0 = *(const f32x4*)(lbl + dir * 1024 + c + 4 * n), z1 = *(const f32x4*)(lbl + 2048 + dir * 1024 + c + 4 * n);
; #pragma unroll
;           for (int j = 0; j < 4; ++j) lb[n][j] = __builtin_amdgcn_rcpf(1.f + __expf(z0[j] - z1[j]));
;         }
; #pragma unroll
;         for (int ai = 0; ai < 2; ++ai)
; #pragma unroll
;           for (int m = 0; m < 4; ++m) if (ai < nai) {
;             const int r = brow + 128 * ai + 64 * wr + 16 * m + fr;
;             h16x8 hv;
; #pragma unroll
;             for (int n = 0; n < 2; ++n) {
;               const f32x4 v = acc[ai][bj][m][n];
; #pragma unroll
;               for (int j = 0; j < 4; ++j) hv[4 * n + j] = (_Float16)(0.6931471805599453f * __builtin_amdgcn_logf(lb[n][j] + (1.f - lb[n][j]) * sigmoidf_(v[j])));
;             }
;             *(h16x8*)(O + (size_t)r * DM + c) = hv;
.LBB0_2126:
	s_andn2_b64 vcc, exec, s[0:1]
	s_cbranch_vccnz .LBB0_2128
	s_add_i32 s4, s4, -2
	s_mul_i32 s0, s4, 0x2100000
	s_mov_b32 s1, s29
	s_lshl_b64 s[0:1], s[0:1], 1
	s_add_u32 s0, s15, s0
	s_addc_u32 s1, s17, s1
	s_lshl_b32 s4, s4, 10
	s_mov_b32 s5, s29
	s_lshl_b64 s[4:5], s[4:5], 2
	s_add_u32 s52, s12, s4
	s_addc_u32 s53, s13, s5
	s_add_u32 s54, s25, s4
	v_lshlrev_b32_e32 v169, 2, v143
	s_addc_u32 s55, s57, s5
	global_load_dwordx4 v[142:145], v169, s[54:55]
	global_load_dwordx4 v[146:149], v169, s[52:53]
	global_load_dwordx4 v[150:153], v169, s[52:53] offset:16
	global_load_dwordx4 v[170:173], v169, s[54:55] offset:16
	global_load_dwordx4 v[236:239], v169, s[54:55] offset:512
	global_load_dwordx4 v[240:243], v169, s[52:53] offset:512
	global_load_dwordx4 v[248:251], v169, s[52:53] offset:528
	global_load_dwordx4 v[252:255], v169, s[54:55] offset:528
	v_mul_f32_e32 v67, 0xbfb8aa3b, v60
	v_mul_f32_e32 v154, 0xbfb8aa3b, v61
	v_mul_f32_e32 v155, 0xbfb8aa3b, v62
	v_mul_f32_e32 v156, 0xbfb8aa3b, v63
	v_mul_f32_e32 v157, 0xbfb8aa3b, v56
	v_exp_f32_e32 v67, v67
	v_exp_f32_e32 v154, v154
	v_exp_f32_e32 v155, v155
	v_exp_f32_e32 v177, v156
	v_exp_f32_e32 v179, v157
	v_lshl_add_u64 v[156:157], s[0:1], 0, v[64:65]
	v_add_f32_e32 v64, 1.0, v67
	v_add_f32_e32 v67, 1.0, v154
	v_add_f32_e32 v154, 1.0, v155
	v_add_f32_e32 v155, 1.0, v177
	v_add_f32_e32 v177, 1.0, v179
	v_rcp_f32_e32 v179, v64
	v_mul_f32_e32 v174, 0xbfb8aa3b, v57
	v_exp_f32_e32 v174, v174
	v_rcp_f32_e32 v67, v67
	v_rcp_f32_e32 v154, v154
	v_mul_f32_e32 v175, 0xbfb8aa3b, v58
	v_add_f32_e32 v174, 1.0, v174
	v_rcp_f32_e32 v188, v174
	v_exp_f32_e32 v175, v175
	v_rcp_f32_e32 v155, v155
	v_rcp_f32_e32 v187, v177
	v_add_f32_e32 v175, 1.0, v175
	v_rcp_f32_e32 v189, v175
	s_waitcnt vmcnt(0)
	v_sub_f32_e32 v64, v146, v142
	v_sub_f32_e32 v142, v147, v143
	v_sub_f32_e32 v143, v148, v144
	v_mul_f32_e32 v64, 0x3fb8aa3b, v64
	v_mul_f32_e32 v142, 0x3fb8aa3b, v142
	v_mul_f32_e32 v143, 0x3fb8aa3b, v143
	v_sub_f32_e32 v144, v149, v145
	v_sub_f32_e32 v145, v150, v170
	v_exp_f32_e32 v64, v64
	v_exp_f32_e32 v142, v142
	v_exp_f32_e32 v143, v143
	v_mul_f32_e32 v144, 0x3fb8aa3b, v144
	v_mul_f32_e32 v145, 0x3fb8aa3b, v145
	v_exp_f32_e32 v144, v144
	v_exp_f32_e32 v145, v145
	v_sub_f32_e32 v147, v152, v172
	v_add_f32_e32 v64, 1.0, v64
	v_add_f32_e32 v142, 1.0, v142
	v_add_f32_e32 v143, 1.0, v143
	v_mul_f32_e32 v147, 0x3fb8aa3b, v147
	v_rcp_f32_e32 v185, v64
	v_rcp_f32_e32 v182, v142
	v_rcp_f32_e32 v181, v143
	v_exp_f32_e32 v147, v147
	v_add_f32_e32 v144, 1.0, v144
	v_add_f32_e32 v145, 1.0, v145
	v_sub_f32_e32 v148, v153, v173
	v_rcp_f32_e32 v174, v144
	v_rcp_f32_e32 v173, v145
	v_sub_f32_e32 v186, 1.0, v185
	v_sub_f32_e32 v184, 1.0, v182
	v_sub_f32_e32 v183, 1.0, v181
	v_sub_f32_e32 v146, v151, v171
	v_add_f32_e32 v147, 1.0, v147
	v_fma_f32 v142, v179, v186, v185
	v_fma_f32 v67, v67, v184, v182
	v_fma_f32 v143, v154, v183, v181
	v_mul_f32_e32 v146, 0x3fb8aa3b, v146
	v_mul_f32_e32 v148, 0x3fb8aa3b, v148
	v_rcp_f32_e32 v170, v147
	v_sub_f32_e32 v180, 1.0, v174
	v_sub_f32_e32 v177, 1.0, v173
	v_log_f32_e32 v147, v142
	v_log_f32_e32 v142, v67
	v_log_f32_e32 v143, v143
	v_exp_f32_e32 v146, v146
	v_exp_f32_e32 v148, v148
	v_fma_f32 v144, v155, v180, v174
	v_fma_f32 v145, v187, v177, v173
	v_log_f32_e32 v144, v144
	v_log_f32_e32 v145, v145
	v_pk_mul_f32 v[142:143], v[142:143], s[40:41] op_sel_hi:[1,0]
	v_add_f32_e32 v146, 1.0, v146
	v_add_f32_e32 v148, 1.0, v148
	v_fma_mixlo_f16 v67, v147, s40, 0
	v_cvt_pk_f16_f32 v142, v142, v143
	v_sub_f32_e32 v175, 1.0, v170
	v_rcp_f32_e32 v171, v146
	v_rcp_f32_e32 v64, v148
	v_pk_mul_f32 v[148:149], v[144:145], s[40:41] op_sel_hi:[1,0]
	v_pack_b32_f16 v144, v67, v142
	v_fma_f32 v67, v189, v175, v170
	v_log_f32_e32 v147, v67
	v_mul_f32_e32 v67, 0xbfb8aa3b, v59
	v_exp_f32_e32 v67, v67
	v_sub_f32_e32 v172, 1.0, v171
	v_fma_f32 v146, v188, v172, v171
	v_log_f32_e32 v146, v146
	v_add_f32_e32 v67, 1.0, v67
	v_rcp_f32_e32 v67, v67
	v_cvt_pk_f16_f32 v148, v148, v149
	v_alignbit_b32 v145, v148, v142, 16
	v_pk_mul_f32 v[142:143], v[146:147], s[40:41] op_sel_hi:[1,0]
	v_sub_f32_e32 v179, 1.0, v64
	v_cvt_pk_f16_f32 v142, v142, v143
	v_fma_f32 v67, v67, v179, v64
	v_alignbit_b32 v146, v142, v148, 16
	v_log_f32_e32 v67, v67
	v_lshrrev_b32_e32 v147, 16, v142
	v_mul_f32_e32 v142, 0xbfb8aa3b, v52
	v_exp_f32_e32 v148, v142
	v_fma_mixhi_f16 v147, v67, s40, 0
	v_ashrrev_i32_e32 v67, 31, v66
	v_lshlrev_b64 v[142:143], 11, v[66:67]
	v_add_f32_e32 v67, 1.0, v148
	v_mul_f32_e32 v148, 0xbfb8aa3b, v53
	v_mul_f32_e32 v149, 0xbfb8aa3b, v54
	v_exp_f32_e32 v148, v148
	v_exp_f32_e32 v149, v149
	v_lshl_add_u64 v[142:143], v[156:157], 0, v[142:143]
	global_store_dwordx4 v[142:143], v[144:147], off
	v_add_f32_e32 v148, 1.0, v148
	v_rcp_f32_e32 v148, v148
	v_add_f32_e32 v145, 1.0, v149
	v_rcp_f32_e32 v145, v145
	v_mul_f32_e32 v146, 0xbfb8aa3b, v55
	v_exp_f32_e32 v146, v146
	v_fma_f32 v144, v148, v184, v182
	v_fma_f32 v145, v145, v183, v181
	v_log_f32_e32 v144, v144
	v_log_f32_e32 v145, v145
	v_add_f32_e32 v146, 1.0, v146
	v_rcp_f32_e32 v146, v146
	v_rcp_f32_e32 v67, v67
	v_pk_mul_f32 v[144:145], v[144:145], s[40:41] op_sel_hi:[1,0]
	v_mul_f32_e32 v147, 0xbfb8aa3b, v48
	v_cvt_pk_f16_f32 v150, v144, v145
	v_fma_f32 v144, v146, v180, v174
	v_mul_f32_e32 v146, 0xbfb8aa3b, v49
	v_exp_f32_e32 v146, v146
	v_exp_f32_e32 v147, v147
	v_fma_f32 v67, v67, v186, v185
	v_log_f32_e32 v67, v67
	v_add_f32_e32 v146, 1.0, v146
	v_add_f32_e32 v145, 1.0, v147
	v_rcp_f32_e32 v147, v146
	v_mul_f32_e32 v146, 0xbfb8aa3b, v50
	v_exp_f32_e32 v148, v146
	v_fma_mixlo_f16 v67, v67, s40, 0
	v_rcp_f32_e32 v145, v145
	v_pack_b32_f16 v146, v67, v150
; __device__ __forceinline__ float sigmoidf_(float a) { return __builtin_amdgcn_rcpf(1.f + __expf(-a)); }
;   __device__ __forceinline__ void operator()(const Acc& acc, int brow, int bcol, int wr, int wc, int fr, int fq, int nai) const {
;     ...
;         for (int ai = 0; ai < 2; ++ai)
; #pragma unroll
;           for (int m = 0; m < 4; ++m) if (ai < nai) {
;             const int r = brow + 128 * ai + 64 * wr + 16 * m + fr;
;             h16x8 hv;
; #pragma unroll
;             for (int n = 0; n < 2; ++n) {
;               const f32x4 v = acc[ai][bj][m][n];
; #pragma unroll
;               for (int j = 0; j < 4; ++j) hv[4 * n + j] = (_Float16)(0.6931471805599453f * __builtin_amdgcn_logf(lb[n][j] + (1.f - lb[n][j]) * sigmoidf_(v[j])));
;             }
;             *(h16x8*)(O + (size_t)r * DM + c) = hv;
	v_fma_f32 v67, v147, v172, v171
	v_add_f32_e32 v147, 1.0, v148
	v_rcp_f32_e32 v147, v147
	v_mul_f32_e32 v148, 0xbfb8aa3b, v51
	v_exp_f32_e32 v151, v148
	v_fma_f32 v145, v145, v177, v173
	v_log_f32_e32 v144, v144
	v_log_f32_e32 v145, v145
	v_log_f32_e32 v148, v67
	v_fma_f32 v67, v147, v175, v170
	v_log_f32_e32 v149, v67
	v_add_f32_e32 v67, 1.0, v151
	v_rcp_f32_e32 v67, v67
	v_pk_mul_f32 v[144:145], v[144:145], s[40:41] op_sel_hi:[1,0]
	v_add_u32_e32 v188, 0x80, v66
	v_cvt_pk_f16_f32 v151, v144, v145
	v_pk_mul_f32 v[144:145], v[148:149], s[40:41] op_sel_hi:[1,0]
	v_fma_f32 v67, v67, v179, v64
	v_cvt_pk_f16_f32 v144, v144, v145
	v_alignbit_b32 v147, v151, v150, 16
	v_log_f32_e32 v67, v67
	v_alignbit_b32 v148, v144, v151, 16
	v_mul_f32_e32 v150, 0xbfb8aa3b, v45
	v_mul_f32_e32 v151, 0xbfb8aa3b, v46
	v_lshrrev_b32_e32 v149, 16, v144
	v_or_b32_e32 v144, 16, v66
	v_exp_f32_e32 v150, v150
	v_exp_f32_e32 v151, v151
	v_ashrrev_i32_e32 v145, 31, v144
	v_lshlrev_b64 v[144:145], 11, v[144:145]
	v_fma_mixhi_f16 v149, v67, s40, 0
	v_lshl_add_u64 v[144:145], v[156:157], 0, v[144:145]
	v_add_f32_e32 v150, 1.0, v150
	global_store_dwordx4 v[144:145], v[146:149], off
	v_rcp_f32_e32 v150, v150
	v_mul_f32_e32 v67, 0xbfb8aa3b, v44
	v_add_f32_e32 v147, 1.0, v151
	v_rcp_f32_e32 v147, v147
	v_mul_f32_e32 v148, 0xbfb8aa3b, v47
	v_exp_f32_e32 v148, v148
	v_fma_f32 v146, v150, v184, v182
	v_fma_f32 v147, v147, v183, v181
	v_log_f32_e32 v146, v146
	v_log_f32_e32 v147, v147
	v_add_f32_e32 v148, 1.0, v148
	v_exp_f32_e32 v67, v67
	v_rcp_f32_e32 v148, v148
	v_pk_mul_f32 v[146:147], v[146:147], s[40:41] op_sel_hi:[1,0]
	v_mul_f32_e32 v149, 0xbfb8aa3b, v40
	v_add_f32_e32 v67, 1.0, v67
	v_cvt_pk_f16_f32 v152, v146, v147
	v_fma_f32 v146, v148, v180, v174
	v_mul_f32_e32 v148, 0xbfb8aa3b, v41
	v_rcp_f32_e32 v67, v67
	v_exp_f32_e32 v148, v148
	v_exp_f32_e32 v149, v149
	v_log_f32_e32 v146, v146
	v_fma_f32 v67, v67, v186, v185
	v_add_f32_e32 v148, 1.0, v148
	v_log_f32_e32 v67, v67
	v_add_f32_e32 v147, 1.0, v149
	v_rcp_f32_e32 v149, v148
	v_mul_f32_e32 v148, 0xbfb8aa3b, v42
	v_exp_f32_e32 v150, v148
	v_fma_mixlo_f16 v67, v67, s40, 0
	v_rcp_f32_e32 v147, v147
	v_pack_b32_f16 v148, v67, v152
	v_fma_f32 v67, v149, v172, v171
	v_add_f32_e32 v149, 1.0, v150
	v_rcp_f32_e32 v149, v149
	v_mul_f32_e32 v150, 0xbfb8aa3b, v43
	v_exp_f32_e32 v153, v150
	v_fma_f32 v147, v147, v177, v173
	v_log_f32_e32 v147, v147
	v_log_f32_e32 v150, v67
	v_fma_f32 v67, v149, v175, v170
	v_log_f32_e32 v151, v67
	v_add_f32_e32 v67, 1.0, v153
	v_rcp_f32_e32 v67, v67
	v_pk_mul_f32 v[146:147], v[146:147], s[40:41] op_sel_hi:[1,0]
	v_ashrrev_i32_e32 v189, 31, v188
	v_cvt_pk_f16_f32 v153, v146, v147
	v_pk_mul_f32 v[146:147], v[150:151], s[40:41] op_sel_hi:[1,0]
	v_fma_f32 v67, v67, v179, v64
	v_cvt_pk_f16_f32 v146, v146, v147
	v_alignbit_b32 v149, v153, v152, 16
	v_log_f32_e32 v67, v67
	v_alignbit_b32 v150, v146, v153, 16
	v_mul_f32_e32 v152, 0xbfb8aa3b, v37
	v_mul_f32_e32 v153, 0xbfb8aa3b, v38
	v_lshrrev_b32_e32 v151, 16, v146
	v_or_b32_e32 v146, 32, v66
	v_exp_f32_e32 v152, v152
	v_exp_f32_e32 v153, v153
	v_ashrrev_i32_e32 v147, 31, v146
	v_lshlrev_b64 v[146:147], 11, v[146:147]
	v_fma_mixhi_f16 v151, v67, s40, 0
	v_lshl_add_u64 v[146:147], v[156:157], 0, v[146:147]
	v_add_f32_e32 v152, 1.0, v152
	global_store_dwordx4 v[146:147], v[148:151], off
	v_rcp_f32_e32 v152, v152
	v_mul_f32_e32 v67, 0xbfb8aa3b, v36
	v_add_f32_e32 v149, 1.0, v153
	v_rcp_f32_e32 v149, v149
	v_mul_f32_e32 v150, 0xbfb8aa3b, v39
	v_exp_f32_e32 v150, v150
	v_fma_f32 v148, v152, v184, v182
	v_fma_f32 v149, v149, v183, v181
	v_log_f32_e32 v148, v148
	v_log_f32_e32 v149, v149
	v_add_f32_e32 v150, 1.0, v150
	v_exp_f32_e32 v67, v67
	v_rcp_f32_e32 v150, v150
	v_pk_mul_f32 v[148:149], v[148:149], s[40:41] op_sel_hi:[1,0]
	v_mul_f32_e32 v151, 0xbfb8aa3b, v32
	v_add_f32_e32 v67, 1.0, v67
	v_cvt_pk_f16_f32 v154, v148, v149
	v_fma_f32 v148, v150, v180, v174
	v_mul_f32_e32 v150, 0xbfb8aa3b, v33
	v_rcp_f32_e32 v67, v67
	v_exp_f32_e32 v150, v150
	v_exp_f32_e32 v151, v151
	v_log_f32_e32 v148, v148
	v_fma_f32 v67, v67, v186, v185
	v_add_f32_e32 v150, 1.0, v150
	v_log_f32_e32 v67, v67
	v_add_f32_e32 v149, 1.0, v151
	v_rcp_f32_e32 v151, v150
	v_mul_f32_e32 v150, 0xbfb8aa3b, v34
	v_exp_f32_e32 v152, v150
	v_fma_mixlo_f16 v67, v67, s40, 0
	v_pack_b32_f16 v150, v67, v154
	v_fma_f32 v67, v151, v172, v171
	v_add_f32_e32 v151, 1.0, v152
	v_rcp_f32_e32 v149, v149
	v_rcp_f32_e32 v151, v151
	v_mul_f32_e32 v152, 0xbfb8aa3b, v35
	v_exp_f32_e32 v155, v152
	v_fma_f32 v149, v149, v177, v173
	v_log_f32_e32 v152, v67
	v_fma_f32 v67, v151, v175, v170
	v_log_f32_e32 v149, v149
	v_log_f32_e32 v153, v67
	v_add_f32_e32 v67, 1.0, v155
	v_rcp_f32_e32 v67, v67
	v_pk_mul_f32 v[148:149], v[148:149], s[40:41] op_sel_hi:[1,0]
	v_fma_f32 v67, v67, v179, v64
	v_cvt_pk_f16_f32 v155, v148, v149
	v_pk_mul_f32 v[148:149], v[152:153], s[40:41] op_sel_hi:[1,0]
	v_log_f32_e32 v67, v67
	v_cvt_pk_f16_f32 v148, v148, v149
	v_alignbit_b32 v152, v148, v155, 16
	v_lshrrev_b32_e32 v153, 16, v148
	v_or_b32_e32 v148, 48, v66
	v_ashrrev_i32_e32 v149, 31, v148
	v_lshlrev_b64 v[148:149], 11, v[148:149]
	v_alignbit_b32 v151, v155, v154, 16
	v_fma_mixhi_f16 v153, v67, s40, 0
	v_lshl_add_u64 v[148:149], v[156:157], 0, v[148:149]
	global_store_dwordx4 v[148:149], v[150:153], off
	v_mul_f32_e32 v67, 0xbfb8aa3b, v128
	v_exp_f32_e32 v67, v67
	v_mul_f32_e32 v150, 0xbfb8aa3b, v129
	v_mul_f32_e32 v151, 0xbfb8aa3b, v130
	v_exp_f32_e32 v150, v150
	v_exp_f32_e32 v151, v151
	v_mul_f32_e32 v152, 0xbfb8aa3b, v131
	v_exp_f32_e32 v152, v152
	v_add_f32_e32 v150, 1.0, v150
	v_add_f32_e32 v151, 1.0, v151
	v_rcp_f32_e32 v150, v150
; __device__ __forceinline__ float sigmoidf_(float a) { return __builtin_amdgcn_rcpf(1.f + __expf(-a)); }
;   __device__ __forceinline__ void operator()(const Acc& acc, int brow, int bcol, int wr, int wc, int fr, int fq, int nai) const {
;     ...
;         for (int ai = 0; ai < 2; ++ai)
; #pragma unroll
;           for (int m = 0; m < 4; ++m) if (ai < nai) {
;             const int r = brow + 128 * ai + 64 * wr + 16 * m + fr;
;             h16x8 hv;
; #pragma unroll
;             for (int n = 0; n < 2; ++n) {
;               const f32x4 v = acc[ai][bj][m][n];
; #pragma unroll
;               for (int j = 0; j < 4; ++j) hv[4 * n + j] = (_Float16)(0.6931471805599453f * __builtin_amdgcn_logf(lb[n][j] + (1.f - lb[n][j]) * sigmoidf_(v[j])));
;             }
;             *(h16x8*)(O + (size_t)r * DM + c) = hv;
	v_rcp_f32_e32 v151, v151
	v_add_f32_e32 v67, 1.0, v67
	v_rcp_f32_e32 v67, v67
	v_fma_f32 v150, v150, v184, v182
	v_fma_f32 v151, v151, v183, v181
	v_add_f32_e32 v152, 1.0, v152
	v_log_f32_e32 v150, v150
	v_log_f32_e32 v151, v151
	v_rcp_f32_e32 v153, v152
	v_mul_f32_e32 v152, 0xbfb8aa3b, v124
	v_fma_f32 v67, v67, v186, v185
	v_exp_f32_e32 v154, v152
	v_log_f32_e32 v67, v67
	v_pk_mul_f32 v[150:151], v[150:151], s[40:41] op_sel_hi:[1,0]
	v_fma_mixlo_f16 v67, v67, s40, 0
	v_cvt_pk_f16_f32 v155, v150, v151
	v_add_f32_e32 v150, 1.0, v154
	v_rcp_f32_e32 v151, v150
	v_mul_f32_e32 v150, 0xbfb8aa3b, v125
	v_pack_b32_f16 v152, v67, v155
	v_fma_f32 v67, v153, v180, v174
	v_exp_f32_e32 v153, v150
	v_log_f32_e32 v150, v67
	v_fma_f32 v67, v151, v177, v173
	v_log_f32_e32 v151, v67
	v_add_f32_e32 v67, 1.0, v153
	v_mul_f32_e32 v153, 0xbfb8aa3b, v126
	v_exp_f32_e32 v153, v153
	v_rcp_f32_e32 v67, v67
	v_pk_mul_f32 v[150:151], v[150:151], s[40:41] op_sel_hi:[1,0]
	v_fma_f32 v67, v67, v172, v171
	v_cvt_pk_f16_f32 v154, v150, v151
	v_add_f32_e32 v150, 1.0, v153
	v_rcp_f32_e32 v151, v150
	v_log_f32_e32 v150, v67
	v_mul_f32_e32 v67, 0xbfb8aa3b, v127
	v_exp_f32_e32 v67, v67
	v_fma_f32 v151, v151, v175, v170
	v_log_f32_e32 v151, v151
	v_alignbit_b32 v153, v154, v155, 16
	v_add_f32_e32 v67, 1.0, v67
	v_rcp_f32_e32 v67, v67
	v_pk_mul_f32 v[150:151], v[150:151], s[40:41] op_sel_hi:[1,0]
	v_fma_f32 v67, v67, v179, v64
	v_cvt_pk_f16_f32 v150, v150, v151
	v_alignbit_b32 v154, v150, v154, 16
	v_lshrrev_b32_e32 v155, 16, v150
	v_mul_f32_e32 v150, 0xbfb8aa3b, v120
	v_log_f32_e32 v67, v67
	v_exp_f32_e32 v187, v150
	v_lshlrev_b64 v[150:151], 11, v[188:189]
	v_mul_f32_e32 v188, 0xbfb8aa3b, v122
	v_fma_mixhi_f16 v155, v67, s40, 0
	v_add_f32_e32 v67, 1.0, v187
	v_mul_f32_e32 v187, 0xbfb8aa3b, v121
	v_exp_f32_e32 v187, v187
	v_exp_f32_e32 v188, v188
	v_lshl_add_u64 v[150:151], v[156:157], 0, v[150:151]
	global_store_dwordx4 v[150:151], v[152:155], off
	v_add_f32_e32 v187, 1.0, v187
	v_rcp_f32_e32 v187, v187
	v_add_f32_e32 v153, 1.0, v188
	v_rcp_f32_e32 v153, v153
	v_mul_f32_e32 v154, 0xbfb8aa3b, v123
	v_exp_f32_e32 v154, v154
	v_fma_f32 v152, v187, v184, v182
	v_fma_f32 v153, v153, v183, v181
	v_log_f32_e32 v152, v152
	v_log_f32_e32 v153, v153
	v_add_f32_e32 v154, 1.0, v154
	v_rcp_f32_e32 v154, v154
	v_rcp_f32_e32 v67, v67
	v_pk_mul_f32 v[152:153], v[152:153], s[40:41] op_sel_hi:[1,0]
	v_mul_f32_e32 v155, 0xbfb8aa3b, v116
	v_cvt_pk_f16_f32 v187, v152, v153
	v_fma_f32 v152, v154, v180, v174
	v_mul_f32_e32 v154, 0xbfb8aa3b, v117
	v_exp_f32_e32 v155, v155
	v_exp_f32_e32 v154, v154
	v_fma_f32 v67, v67, v186, v185
	v_log_f32_e32 v67, v67
	v_add_f32_e32 v153, 1.0, v155
	v_add_f32_e32 v154, 1.0, v154
	v_mul_f32_e32 v155, 0xbfb8aa3b, v118
	v_rcp_f32_e32 v154, v154
	v_exp_f32_e32 v155, v155
	v_fma_mixlo_f16 v67, v67, s40, 0
	v_rcp_f32_e32 v153, v153
	v_pack_b32_f16 v188, v67, v187
	v_fma_f32 v67, v154, v172, v171
	v_add_f32_e32 v154, 1.0, v155
	v_rcp_f32_e32 v155, v154
	v_fma_f32 v153, v153, v177, v173
	v_mul_f32_e32 v154, 0xbfb8aa3b, v119
	v_log_f32_e32 v152, v152
	v_log_f32_e32 v153, v153
	v_exp_f32_e32 v189, v154
	v_log_f32_e32 v154, v67
	v_fma_f32 v67, v155, v175, v170
	v_log_f32_e32 v155, v67
	v_pk_mul_f32 v[152:153], v[152:153], s[40:41] op_sel_hi:[1,0]
	v_add_f32_e32 v67, 1.0, v189
	v_cvt_pk_f16_f32 v190, v152, v153
	v_pk_mul_f32 v[152:153], v[154:155], s[40:41] op_sel_hi:[1,0]
	v_mul_f32_e32 v154, 0xbfb8aa3b, v113
	v_mul_f32_e32 v155, 0xbfb8aa3b, v114
	v_rcp_f32_e32 v67, v67
	v_exp_f32_e32 v154, v154
	v_exp_f32_e32 v155, v155
	v_alignbit_b32 v189, v190, v187, 16
	v_fma_f32 v67, v67, v179, v64
	v_add_f32_e32 v154, 1.0, v154
	v_add_f32_e32 v155, 1.0, v155
	v_log_f32_e32 v67, v67
	v_rcp_f32_e32 v154, v154
	v_rcp_f32_e32 v155, v155
	v_mul_f32_e32 v187, 0xbfb8aa3b, v115
	v_exp_f32_e32 v187, v187
	v_cvt_pk_f16_f32 v152, v152, v153
	v_lshrrev_b32_e32 v191, 16, v152
	v_fma_mixhi_f16 v191, v67, s40, 0
	v_mul_f32_e32 v67, 0xbfb8aa3b, v112
	v_fma_f32 v154, v154, v184, v182
	v_fma_f32 v155, v155, v183, v181
	v_exp_f32_e32 v67, v67
	v_log_f32_e32 v154, v154
	v_log_f32_e32 v155, v155
	v_add_f32_e32 v187, 1.0, v187
	v_alignbit_b32 v190, v152, v190, 16
	v_add_u32_e32 v152, 0x90, v66
	v_rcp_f32_e32 v187, v187
	v_ashrrev_i32_e32 v153, 31, v152
	v_lshlrev_b64 v[152:153], 11, v[152:153]
	v_add_f32_e32 v67, 1.0, v67
	v_lshl_add_u64 v[152:153], v[156:157], 0, v[152:153]
	v_pk_mul_f32 v[154:155], v[154:155], s[40:41] op_sel_hi:[1,0]
	v_rcp_f32_e32 v67, v67
	global_store_dwordx4 v[152:153], v[188:191], off
	v_fma_f32 v67, v67, v186, v185
	s_nop 0
	v_mul_f32_e32 v188, 0xbfb8aa3b, v108
	v_cvt_pk_f16_f32 v189, v154, v155
	v_fma_f32 v154, v187, v180, v174
	v_mul_f32_e32 v187, 0xbfb8aa3b, v109
	v_exp_f32_e32 v188, v188
	v_exp_f32_e32 v187, v187
	v_log_f32_e32 v67, v67
	v_log_f32_e32 v154, v154
	v_add_f32_e32 v155, 1.0, v188
	v_add_f32_e32 v187, 1.0, v187
	v_mul_f32_e32 v188, 0xbfb8aa3b, v110
	v_rcp_f32_e32 v187, v187
	v_exp_f32_e32 v190, v188
	v_fma_mixlo_f16 v67, v67, s40, 0
	v_pack_b32_f16 v188, v67, v189
	v_fma_f32 v67, v187, v172, v171
	v_add_f32_e32 v187, 1.0, v190
	v_rcp_f32_e32 v187, v187
	v_mul_f32_e32 v190, 0xbfb8aa3b, v111
	v_exp_f32_e32 v192, v190
	v_rcp_f32_e32 v155, v155
	v_log_f32_e32 v190, v67
	v_fma_f32 v67, v187, v175, v170
	v_log_f32_e32 v191, v67
	v_add_f32_e32 v67, 1.0, v192
	v_fma_f32 v155, v155, v177, v173
	v_rcp_f32_e32 v67, v67
	v_log_f32_e32 v155, v155
	v_fma_f32 v67, v67, v179, v64
	v_pk_mul_f32 v[154:155], v[154:155], s[40:41] op_sel_hi:[1,0]
	v_log_f32_e32 v67, v67
	v_cvt_pk_f16_f32 v187, v154, v155
	v_pk_mul_f32 v[154:155], v[190:191], s[40:41] op_sel_hi:[1,0]
; __device__ __forceinline__ float sigmoidf_(float a) { return __builtin_amdgcn_rcpf(1.f + __expf(-a)); }
;   __device__ __forceinline__ void operator()(const Acc& acc, int brow, int bcol, int wr, int wc, int fr, int fq, int nai) const {
;     ...
;       for (int bj = 0; bj < 2; ++bj) {
;         const int c = cb + 128 * bj;
;         f32x4 lb[2];
; #pragma unroll
;         for (int n = 0; n < 2; ++n) {
;           const f32x4 z0 = *(const f32x4*)(lbl + dir * 1024 + c + 4 * n), z1 = *(const f32x4*)(lbl + 2048 + dir * 1024 + c + 4 * n);
; #pragma unroll
;           for (int j = 0; j < 4; ++j) lb[n][j] = __builtin_amdgcn_rcpf(1.f + __expf(z0[j] - z1[j]));
;         }
; #pragma unroll
;         for (int ai = 0; ai < 2; ++ai)
; #pragma unroll
;           for (int m = 0; m < 4; ++m) if (ai < nai) {
;             const int r = brow + 128 * ai + 64 * wr + 16 * m + fr;
;             h16x8 hv;
; #pragma unroll
;             for (int n = 0; n < 2; ++n) {
;               const f32x4 v = acc[ai][bj][m][n];
; #pragma unroll
;               for (int j = 0; j < 4; ++j) hv[4 * n + j] = (_Float16)(0.6931471805599453f * __builtin_amdgcn_logf(lb[n][j] + (1.f - lb[n][j]) * sigmoidf_(v[j])));
;             }
;             *(h16x8*)(O + (size_t)r * DM + c) = hv;
	v_alignbit_b32 v189, v187, v189, 16
	v_cvt_pk_f16_f32 v154, v154, v155
	v_lshrrev_b32_e32 v191, 16, v154
	v_fma_mixhi_f16 v191, v67, s40, 0
	v_mul_f32_e32 v67, 0xbfb8aa3b, v104
	v_exp_f32_e32 v67, v67
	v_alignbit_b32 v190, v154, v187, 16
	v_mul_f32_e32 v187, 0xbfb8aa3b, v105
	v_exp_f32_e32 v187, v187
	v_add_f32_e32 v67, 1.0, v67
	v_rcp_f32_e32 v67, v67
	v_add_u32_e32 v154, 0xa0, v66
	v_add_u32_e32 v66, 0xb0, v66
	v_ashrrev_i32_e32 v155, 31, v154
	v_fmac_f32_e32 v185, v67, v186
	v_log_f32_e32 v67, v185
	v_add_f32_e32 v185, 1.0, v187
	v_mul_f32_e32 v186, 0xbfb8aa3b, v106
	v_rcp_f32_e32 v185, v185
	v_exp_f32_e32 v186, v186
	v_fma_mixlo_f16 v67, v67, s40, 0
	v_lshlrev_b64 v[154:155], 11, v[154:155]
	v_fmac_f32_e32 v182, v185, v184
	v_add_f32_e32 v184, 1.0, v186
	v_rcp_f32_e32 v184, v184
	v_mul_f32_e32 v185, 0xbfb8aa3b, v107
	v_exp_f32_e32 v185, v185
	v_log_f32_e32 v182, v182
	v_fmac_f32_e32 v181, v184, v183
	v_log_f32_e32 v183, v181
	v_add_f32_e32 v181, 1.0, v185
	v_mul_f32_e32 v184, 0xbfb8aa3b, v100
	v_rcp_f32_e32 v181, v181
	v_exp_f32_e32 v184, v184
	v_pk_mul_f32 v[182:183], v[182:183], s[40:41] op_sel_hi:[1,0]
	v_lshl_add_u64 v[154:155], v[156:157], 0, v[154:155]
	v_fmac_f32_e32 v174, v181, v180
	v_add_f32_e32 v180, 1.0, v184
	v_rcp_f32_e32 v180, v180
	v_mul_f32_e32 v181, 0xbfb8aa3b, v101
	v_exp_f32_e32 v181, v181
	v_cvt_pk_f16_f32 v185, v182, v183
	v_fmac_f32_e32 v173, v180, v177
	v_log_f32_e32 v182, v174
	v_log_f32_e32 v183, v173
	v_add_f32_e32 v173, 1.0, v181
	v_mul_f32_e32 v174, 0xbfb8aa3b, v102
	v_rcp_f32_e32 v173, v173
	v_exp_f32_e32 v174, v174
	v_pack_b32_f16 v180, v67, v185
	v_pk_mul_f32 v[182:183], v[182:183], s[40:41] op_sel_hi:[1,0]
	v_fmac_f32_e32 v171, v173, v172
	v_add_f32_e32 v67, 1.0, v174
	v_mul_f32_e32 v172, 0xbfb8aa3b, v103
	v_rcp_f32_e32 v67, v67
	v_exp_f32_e32 v174, v172
	v_log_f32_e32 v172, v171
	global_store_dwordx4 v[154:155], v[188:191], off
	v_fmac_f32_e32 v170, v67, v175
	v_add_f32_e32 v67, 1.0, v174
	v_rcp_f32_e32 v67, v67
	v_log_f32_e32 v173, v170
	v_cvt_pk_f16_f32 v174, v182, v183
	v_alignbit_b32 v181, v174, v185, 16
	v_fmac_f32_e32 v64, v67, v179
	v_pk_mul_f32 v[170:171], v[172:173], s[40:41] op_sel_hi:[1,0]
	v_log_f32_e32 v64, v64
	v_cvt_pk_f16_f32 v67, v170, v171
	v_alignbit_b32 v182, v67, v174, 16
	v_lshrrev_b32_e32 v183, 16, v67
	v_ashrrev_i32_e32 v67, 31, v66
	v_lshlrev_b64 v[66:67], 11, v[66:67]
	v_fma_mixhi_f16 v183, v64, s40, 0
	v_lshl_add_u64 v[66:67], v[156:157], 0, v[66:67]
	global_store_dwordx4 v[66:67], v[180:183], off
	v_mov_b32_e32 v172, v236
	v_mov_b32_e32 v173, v237
	v_mov_b32_e32 v174, v238
	v_mov_b32_e32 v175, v239
	v_mov_b32_e32 v180, v240
	v_mov_b32_e32 v181, v241
	v_mov_b32_e32 v182, v242
	v_mov_b32_e32 v183, v243
	v_mov_b32_e32 v184, v248
	v_mov_b32_e32 v185, v249
	v_mov_b32_e32 v186, v250
	v_mov_b32_e32 v187, v251
	v_mov_b32_e32 v188, v252
	v_mov_b32_e32 v189, v253
	v_mov_b32_e32 v190, v254
	v_mov_b32_e32 v191, v255
	v_sub_f32_e32 v64, v180, v172
	v_mul_f32_e32 v64, 0x3fb8aa3b, v64
	v_sub_f32_e32 v156, v181, v173
	v_exp_f32_e32 v64, v64
	v_mul_f32_e32 v156, 0x3fb8aa3b, v156
	v_exp_f32_e32 v156, v156
	v_sub_f32_e32 v157, v183, v175
	v_add_f32_e32 v64, 1.0, v64
	v_rcp_f32_e32 v173, v64
	v_add_f32_e32 v64, 1.0, v156
	v_sub_f32_e32 v156, v182, v174
	v_mul_f32_e32 v156, 0x3fb8aa3b, v156
	v_exp_f32_e32 v156, v156
	v_mul_f32_e32 v157, 0x3fb8aa3b, v157
	v_exp_f32_e32 v157, v157
	v_rcp_f32_e32 v170, v64
	v_add_f32_e32 v64, 1.0, v156
	v_sub_f32_e32 v156, v184, v188
	v_rcp_f32_e32 v171, v64
	v_add_f32_e32 v64, 1.0, v157
	v_mul_f32_e32 v156, 0x3fb8aa3b, v156
	v_sub_f32_e32 v157, v185, v189
	v_exp_f32_e32 v156, v156
	v_mul_f32_e32 v157, 0x3fb8aa3b, v157
	v_exp_f32_e32 v172, v157
	v_rcp_f32_e32 v157, v64
	v_add_f32_e32 v64, 1.0, v156
	v_rcp_f32_e32 v169, v64
	v_add_f32_e32 v64, 1.0, v172
	v_mul_f32_e32 v172, 0xbfb8aa3b, v28
	v_exp_f32_e32 v172, v172
	v_sub_f32_e32 v174, v187, v191
	v_mul_f32_e32 v174, 0x3fb8aa3b, v174
	v_exp_f32_e32 v177, v174
	v_add_f32_e32 v172, 1.0, v172
	v_rcp_f32_e32 v172, v172
	v_sub_f32_e32 v175, 1.0, v173
	v_mul_f32_e32 v174, 0xbfb8aa3b, v29
	v_exp_f32_e32 v174, v174
	v_fma_f32 v172, v172, v175, v173
	v_log_f32_e32 v179, v172
	v_mul_f32_e32 v172, 0xbfb8aa3b, v30
	v_exp_f32_e32 v172, v172
	v_add_f32_e32 v174, 1.0, v174
	v_rcp_f32_e32 v174, v174
	v_sub_f32_e32 v180, 1.0, v170
	v_add_f32_e32 v172, 1.0, v172
	v_rcp_f32_e32 v172, v172
	v_fma_f32 v174, v174, v180, v170
	v_log_f32_e32 v182, v174
	v_sub_f32_e32 v174, 1.0, v171
	v_fma_f32 v172, v172, v174, v171
	v_log_f32_e32 v183, v172
	v_add_f32_e32 v172, 1.0, v177
	v_fma_mixlo_f16 v177, v179, s40, 0
	v_mul_f32_e32 v179, 0xbfb8aa3b, v31
	v_pk_mul_f32 v[182:183], v[182:183], s[40:41] op_sel_hi:[1,0]
	v_exp_f32_e32 v179, v179
	v_cvt_pk_f16_f32 v183, v182, v183
	v_pack_b32_f16 v184, v177, v183
	v_mul_f32_e32 v177, 0xbfb8aa3b, v24
	v_exp_f32_e32 v177, v177
	v_add_f32_e32 v179, 1.0, v179
	v_rcp_f32_e32 v179, v179
	v_sub_f32_e32 v181, 1.0, v157
	v_add_f32_e32 v177, 1.0, v177
	v_rcp_f32_e32 v182, v177
	v_fma_f32 v177, v179, v181, v157
	v_sub_f32_e32 v156, v186, v190
	v_log_f32_e32 v186, v177
	v_sub_f32_e32 v177, 1.0, v169
	v_fma_f32 v179, v182, v177, v169
	v_mul_f32_e32 v182, 0xbfb8aa3b, v25
	v_mul_f32_e32 v156, 0x3fb8aa3b, v156
	v_exp_f32_e32 v182, v182
	v_exp_f32_e32 v156, v156
	v_log_f32_e32 v187, v179
	v_mul_f32_e32 v179, 0xbfb8aa3b, v26
	v_exp_f32_e32 v179, v179
	v_rcp_f32_e32 v64, v64
	v_add_f32_e32 v182, 1.0, v182
	v_add_f32_e32 v156, 1.0, v156
	v_rcp_f32_e32 v185, v182
	v_rcp_f32_e32 v156, v156
	v_add_f32_e32 v179, 1.0, v179
	v_rcp_f32_e32 v189, v179
	v_sub_f32_e32 v182, 1.0, v64
	v_fma_f32 v179, v185, v182, v64
; __device__ __forceinline__ float sigmoidf_(float a) { return __builtin_amdgcn_rcpf(1.f + __expf(-a)); }
;   __device__ __forceinline__ void operator()(const Acc& acc, int brow, int bcol, int wr, int wc, int fr, int fq, int nai) const {
;     ...
;         for (int ai = 0; ai < 2; ++ai)
; #pragma unroll
;           for (int m = 0; m < 4; ++m) if (ai < nai) {
;             const int r = brow + 128 * ai + 64 * wr + 16 * m + fr;
;             h16x8 hv;
; #pragma unroll
;             for (int n = 0; n < 2; ++n) {
;               const f32x4 v = acc[ai][bj][m][n];
; #pragma unroll
;               for (int j = 0; j < 4; ++j) hv[4 * n + j] = (_Float16)(0.6931471805599453f * __builtin_amdgcn_logf(lb[n][j] + (1.f - lb[n][j]) * sigmoidf_(v[j])));
;             }
;             *(h16x8*)(O + (size_t)r * DM + c) = hv;
	v_log_f32_e32 v188, v179
	v_sub_f32_e32 v179, 1.0, v156
	v_pk_mul_f32 v[186:187], v[186:187], s[40:41] op_sel_hi:[1,0]
	v_fma_f32 v185, v189, v179, v156
	v_cvt_pk_f16_f32 v190, v186, v187
	v_log_f32_e32 v189, v185
	v_alignbit_b32 v185, v190, v183, 16
	v_mul_f32_e32 v183, 0xbfb8aa3b, v27
	v_exp_f32_e32 v183, v183
	v_rcp_f32_e32 v172, v172
	v_pk_mul_f32 v[186:187], v[188:189], s[40:41] op_sel_hi:[1,0]
	v_mul_f32_e32 v191, 0xbfb8aa3b, v22
	v_add_f32_e32 v183, 1.0, v183
	v_rcp_f32_e32 v188, v183
	v_mul_f32_e32 v183, 0xbfb8aa3b, v20
	v_exp_f32_e32 v189, v183
	v_sub_f32_e32 v183, 1.0, v172
	v_cvt_pk_f16_f32 v187, v186, v187
	v_fma_f32 v188, v188, v183, v172
	v_alignbit_b32 v186, v187, v190, 16
	v_log_f32_e32 v190, v188
	v_add_f32_e32 v188, 1.0, v189
	v_mul_f32_e32 v189, 0xbfb8aa3b, v21
	v_exp_f32_e32 v189, v189
	v_exp_f32_e32 v191, v191
	v_rcp_f32_e32 v188, v188
	v_lshrrev_b32_e32 v187, 16, v187
	v_add_f32_e32 v189, 1.0, v189
	v_add_f32_e32 v191, 1.0, v191
	v_rcp_f32_e32 v189, v189
	v_rcp_f32_e32 v191, v191
	v_fma_f32 v188, v188, v175, v173
	v_log_f32_e32 v192, v188
	v_fma_f32 v188, v189, v180, v170
	v_fma_f32 v189, v191, v174, v171
	v_fma_mixhi_f16 v187, v190, s40, 0
	v_log_f32_e32 v188, v188
	v_log_f32_e32 v189, v189
	global_store_dwordx4 v[142:143], v[184:187], off offset:256
	v_pk_mul_f32 v[142:143], v[188:189], s[40:41] op_sel_hi:[1,0]
	s_nop 0
	v_mul_f32_e32 v185, 0xbfb8aa3b, v23
	v_mul_f32_e32 v186, 0xbfb8aa3b, v16
	v_exp_f32_e32 v185, v185
	v_exp_f32_e32 v186, v186
	v_cvt_pk_f16_f32 v187, v142, v143
	v_fma_mixlo_f16 v184, v192, s40, 0
	v_add_f32_e32 v142, 1.0, v185
	v_add_f32_e32 v143, 1.0, v186
	v_rcp_f32_e32 v142, v142
	v_rcp_f32_e32 v143, v143
	v_mul_f32_e32 v185, 0xbfb8aa3b, v17
	v_mul_f32_e32 v186, 0xbfb8aa3b, v18
	v_exp_f32_e32 v185, v185
	v_exp_f32_e32 v186, v186
	v_fma_f32 v142, v142, v181, v157
	v_fma_f32 v143, v143, v177, v169
	v_log_f32_e32 v142, v142
	v_log_f32_e32 v143, v143
	v_add_f32_e32 v185, 1.0, v185
	v_add_f32_e32 v186, 1.0, v186
	v_rcp_f32_e32 v185, v185
	v_rcp_f32_e32 v186, v186
	v_pk_mul_f32 v[142:143], v[142:143], s[40:41] op_sel_hi:[1,0]
	v_pack_b32_f16 v184, v184, v187
	v_cvt_pk_f16_f32 v188, v142, v143
	v_fma_f32 v142, v185, v182, v64
	v_fma_f32 v143, v186, v179, v156
	v_log_f32_e32 v142, v142
	v_log_f32_e32 v143, v143
	v_mul_f32_e32 v186, 0xbfb8aa3b, v19
	v_alignbit_b32 v185, v188, v187, 16
	v_exp_f32_e32 v187, v186
	v_pk_mul_f32 v[142:143], v[142:143], s[40:41] op_sel_hi:[1,0]
	s_nop 0
	v_cvt_pk_f16_f32 v142, v142, v143
	v_add_f32_e32 v143, 1.0, v187
	v_rcp_f32_e32 v143, v143
	v_mul_f32_e32 v187, 0xbfb8aa3b, v12
	v_alignbit_b32 v186, v142, v188, 16
	v_exp_f32_e32 v188, v187
	v_lshrrev_b32_e32 v187, 16, v142
	v_fma_f32 v142, v143, v183, v172
	v_log_f32_e32 v189, v142
	v_add_f32_e32 v142, 1.0, v188
	v_mul_f32_e32 v143, 0xbfb8aa3b, v13
	v_mul_f32_e32 v188, 0xbfb8aa3b, v14
	v_exp_f32_e32 v143, v143
	v_exp_f32_e32 v188, v188
	v_rcp_f32_e32 v142, v142
	v_fma_mixhi_f16 v187, v189, s40, 0
	v_add_f32_e32 v143, 1.0, v143
	v_add_f32_e32 v188, 1.0, v188
	v_rcp_f32_e32 v143, v143
	v_rcp_f32_e32 v188, v188
	v_fma_f32 v142, v142, v175, v173
	v_log_f32_e32 v190, v142
	v_fma_f32 v142, v143, v180, v170
	v_fma_f32 v143, v188, v174, v171
	v_log_f32_e32 v142, v142
	v_log_f32_e32 v143, v143
	global_store_dwordx4 v[144:145], v[184:187], off offset:256
	v_mul_f32_e32 v145, 0xbfb8aa3b, v15
	v_exp_f32_e32 v145, v145
	v_mul_f32_e32 v184, 0xbfb8aa3b, v8
	v_exp_f32_e32 v184, v184
	v_pk_mul_f32 v[142:143], v[142:143], s[40:41] op_sel_hi:[1,0]
	v_fma_mixlo_f16 v144, v190, s40, 0
	v_cvt_pk_f16_f32 v143, v142, v143
	v_add_f32_e32 v142, 1.0, v145
	v_rcp_f32_e32 v145, v142
	v_add_f32_e32 v142, 1.0, v184
	v_rcp_f32_e32 v184, v142
	v_pack_b32_f16 v142, v144, v143
	v_fma_f32 v144, v145, v181, v157
	v_mul_f32_e32 v185, 0xbfb8aa3b, v10
	v_fma_f32 v145, v184, v177, v169
	v_mul_f32_e32 v184, 0xbfb8aa3b, v9
	v_exp_f32_e32 v184, v184
	v_log_f32_e32 v144, v144
	v_log_f32_e32 v145, v145
	v_exp_f32_e32 v185, v185
	v_add_f32_e32 v184, 1.0, v184
	v_rcp_f32_e32 v184, v184
	v_pk_mul_f32 v[144:145], v[144:145], s[40:41] op_sel_hi:[1,0]
	v_add_f32_e32 v185, 1.0, v185
	v_rcp_f32_e32 v185, v185
	v_cvt_pk_f16_f32 v186, v144, v145
	v_fma_f32 v144, v184, v182, v64
	v_mul_f32_e32 v184, 0xbfb8aa3b, v11
	v_exp_f32_e32 v184, v184
	v_fma_f32 v145, v185, v179, v156
	v_log_f32_e32 v144, v144
	v_log_f32_e32 v145, v145
	v_add_f32_e32 v184, 1.0, v184
	v_rcp_f32_e32 v184, v184
	v_mul_f32_e32 v185, 0xbfb8aa3b, v4
	v_exp_f32_e32 v185, v185
	v_pk_mul_f32 v[144:145], v[144:145], s[40:41] op_sel_hi:[1,0]
	v_fma_f32 v184, v184, v183, v172
	v_cvt_pk_f16_f32 v145, v144, v145
	v_alignbit_b32 v143, v186, v143, 16
	v_alignbit_b32 v144, v145, v186, 16
	v_log_f32_e32 v186, v184
	v_add_f32_e32 v184, 1.0, v185
	v_mul_f32_e32 v185, 0xbfb8aa3b, v5
	v_mul_f32_e32 v187, 0xbfb8aa3b, v6
	v_exp_f32_e32 v185, v185
	v_exp_f32_e32 v187, v187
	v_rcp_f32_e32 v184, v184
	v_lshrrev_b32_e32 v145, 16, v145
	v_add_f32_e32 v185, 1.0, v185
	v_add_f32_e32 v187, 1.0, v187
	v_rcp_f32_e32 v185, v185
	v_rcp_f32_e32 v187, v187
	v_fma_f32 v184, v184, v175, v173
	v_log_f32_e32 v188, v184
	v_fma_f32 v184, v185, v180, v170
	v_fma_f32 v185, v187, v174, v171
	v_fma_mixhi_f16 v145, v186, s40, 0
	v_log_f32_e32 v184, v184
	v_log_f32_e32 v185, v185
	global_store_dwordx4 v[146:147], v[142:145], off offset:256
	v_mul_f32_e32 v146, 0xbfb8aa3b, v0
	v_exp_f32_e32 v146, v146
	v_mul_f32_e32 v145, 0xbfb8aa3b, v7
	v_exp_f32_e32 v145, v145
	v_pk_mul_f32 v[142:143], v[184:185], s[40:41] op_sel_hi:[1,0]
	v_fma_mixlo_f16 v144, v188, s40, 0
	v_cvt_pk_f16_f32 v143, v142, v143
	v_add_f32_e32 v142, 1.0, v145
	v_rcp_f32_e32 v145, v142
; __device__ __forceinline__ float sigmoidf_(float a) { return __builtin_amdgcn_rcpf(1.f + __expf(-a)); }
;   __device__ __forceinline__ void operator()(const Acc& acc, int brow, int bcol, int wr, int wc, int fr, int fq, int nai) const {
;     ...
;         for (int ai = 0; ai < 2; ++ai)
; #pragma unroll
;           for (int m = 0; m < 4; ++m) if (ai < nai) {
;             const int r = brow + 128 * ai + 64 * wr + 16 * m + fr;
;             h16x8 hv;
; #pragma unroll
;             for (int n = 0; n < 2; ++n) {
;               const f32x4 v = acc[ai][bj][m][n];
; #pragma unroll
;               for (int j = 0; j < 4; ++j) hv[4 * n + j] = (_Float16)(0.6931471805599453f * __builtin_amdgcn_logf(lb[n][j] + (1.f - lb[n][j]) * sigmoidf_(v[j])));
;             }
;             *(h16x8*)(O + (size_t)r * DM + c) = hv;
	v_add_f32_e32 v142, 1.0, v146
	v_rcp_f32_e32 v146, v142
	v_pack_b32_f16 v142, v144, v143
	v_fma_f32 v144, v145, v181, v157
	v_mul_f32_e32 v147, 0xbfb8aa3b, v2
	v_fma_f32 v145, v146, v177, v169
	v_mul_f32_e32 v146, 0xbfb8aa3b, v1
	v_exp_f32_e32 v146, v146
	v_log_f32_e32 v144, v144
	v_log_f32_e32 v145, v145
	v_exp_f32_e32 v147, v147
	v_add_f32_e32 v146, 1.0, v146
	v_rcp_f32_e32 v146, v146
	v_pk_mul_f32 v[144:145], v[144:145], s[40:41] op_sel_hi:[1,0]
	v_add_f32_e32 v147, 1.0, v147
	v_rcp_f32_e32 v147, v147
	v_cvt_pk_f16_f32 v184, v144, v145
	v_fma_f32 v144, v146, v182, v64
	v_mul_f32_e32 v146, 0xbfb8aa3b, v3
	v_exp_f32_e32 v146, v146
	v_fma_f32 v145, v147, v179, v156
	v_log_f32_e32 v144, v144
	v_log_f32_e32 v145, v145
	v_add_f32_e32 v146, 1.0, v146
	v_rcp_f32_e32 v146, v146
	v_mul_f32_e32 v147, 0xbfb8aa3b, v96
	v_exp_f32_e32 v147, v147
	v_pk_mul_f32 v[144:145], v[144:145], s[40:41] op_sel_hi:[1,0]
	v_fma_f32 v146, v146, v183, v172
	v_cvt_pk_f16_f32 v145, v144, v145
	v_alignbit_b32 v143, v184, v143, 16
	v_alignbit_b32 v144, v145, v184, 16
	v_log_f32_e32 v184, v146
	v_add_f32_e32 v146, 1.0, v147
	v_mul_f32_e32 v147, 0xbfb8aa3b, v97
	v_mul_f32_e32 v185, 0xbfb8aa3b, v98
	v_exp_f32_e32 v147, v147
	v_exp_f32_e32 v185, v185
	v_rcp_f32_e32 v146, v146
	v_lshrrev_b32_e32 v145, 16, v145
	v_add_f32_e32 v147, 1.0, v147
	v_add_f32_e32 v185, 1.0, v185
	v_rcp_f32_e32 v147, v147
	v_rcp_f32_e32 v185, v185
	v_fma_f32 v146, v146, v175, v173
	v_log_f32_e32 v186, v146
	v_fma_f32 v146, v147, v180, v170
	v_fma_f32 v147, v185, v174, v171
	v_log_f32_e32 v146, v146
	v_log_f32_e32 v147, v147
	v_fma_mixhi_f16 v145, v184, s40, 0
	global_store_dwordx4 v[148:149], v[142:145], off offset:256
	v_mul_f32_e32 v149, 0xbfb8aa3b, v90
	v_exp_f32_e32 v149, v149
	v_mul_f32_e32 v145, 0xbfb8aa3b, v99
	v_pk_mul_f32 v[142:143], v[146:147], s[40:41] op_sel_hi:[1,0]
	v_exp_f32_e32 v145, v145
	v_mul_f32_e32 v146, 0xbfb8aa3b, v92
	v_exp_f32_e32 v146, v146
	v_cvt_pk_f16_f32 v143, v142, v143
	v_add_f32_e32 v142, 1.0, v145
	v_rcp_f32_e32 v145, v142
	v_add_f32_e32 v142, 1.0, v146
	v_rcp_f32_e32 v146, v142
	v_fma_mixlo_f16 v144, v186, s40, 0
	v_pack_b32_f16 v142, v144, v143
	v_fma_f32 v144, v145, v181, v157
	v_fma_f32 v145, v146, v177, v169
	v_mul_f32_e32 v146, 0xbfb8aa3b, v93
	v_exp_f32_e32 v146, v146
	v_mul_f32_e32 v147, 0xbfb8aa3b, v94
	v_log_f32_e32 v144, v144
	v_log_f32_e32 v145, v145
	v_exp_f32_e32 v147, v147
	v_add_f32_e32 v146, 1.0, v146
	v_rcp_f32_e32 v146, v146
	v_pk_mul_f32 v[144:145], v[144:145], s[40:41] op_sel_hi:[1,0]
	v_add_f32_e32 v147, 1.0, v147
	v_rcp_f32_e32 v147, v147
	v_cvt_pk_f16_f32 v148, v144, v145
	v_fma_f32 v144, v146, v182, v64
	v_mul_f32_e32 v146, 0xbfb8aa3b, v95
	v_exp_f32_e32 v146, v146
	v_fma_f32 v145, v147, v179, v156
	v_log_f32_e32 v144, v144
	v_log_f32_e32 v145, v145
	v_add_f32_e32 v146, 1.0, v146
	v_rcp_f32_e32 v146, v146
	v_mul_f32_e32 v147, 0xbfb8aa3b, v88
	v_exp_f32_e32 v147, v147
	v_pk_mul_f32 v[144:145], v[144:145], s[40:41] op_sel_hi:[1,0]
	v_fma_f32 v146, v146, v183, v172
	v_cvt_pk_f16_f32 v145, v144, v145
	v_alignbit_b32 v143, v148, v143, 16
	v_alignbit_b32 v144, v145, v148, 16
	v_log_f32_e32 v148, v146
	v_add_f32_e32 v146, 1.0, v147
	v_mul_f32_e32 v147, 0xbfb8aa3b, v89
	v_exp_f32_e32 v147, v147
	v_rcp_f32_e32 v146, v146
	v_add_f32_e32 v149, 1.0, v149
	v_rcp_f32_e32 v149, v149
	v_add_f32_e32 v147, 1.0, v147
	v_rcp_f32_e32 v147, v147
	v_fma_f32 v146, v146, v175, v173
	v_log_f32_e32 v184, v146
	v_lshrrev_b32_e32 v145, 16, v145
	v_fma_f32 v146, v147, v180, v170
	v_fma_f32 v147, v149, v174, v171
	v_log_f32_e32 v146, v146
	v_log_f32_e32 v147, v147
	v_fma_mixhi_f16 v145, v148, s40, 0
	global_store_dwordx4 v[150:151], v[142:145], off offset:256
	v_mul_f32_e32 v149, 0xbfb8aa3b, v82
	v_exp_f32_e32 v149, v149
	v_mul_f32_e32 v145, 0xbfb8aa3b, v91
	v_pk_mul_f32 v[142:143], v[146:147], s[40:41] op_sel_hi:[1,0]
	v_exp_f32_e32 v145, v145
	v_mul_f32_e32 v146, 0xbfb8aa3b, v84
	v_exp_f32_e32 v146, v146
	v_cvt_pk_f16_f32 v143, v142, v143
	v_add_f32_e32 v142, 1.0, v145
	v_rcp_f32_e32 v145, v142
	v_add_f32_e32 v142, 1.0, v146
	v_rcp_f32_e32 v146, v142
	v_fma_mixlo_f16 v144, v184, s40, 0
	v_pack_b32_f16 v142, v144, v143
	v_fma_f32 v144, v145, v181, v157
	v_fma_f32 v145, v146, v177, v169
	v_mul_f32_e32 v146, 0xbfb8aa3b, v85
	v_exp_f32_e32 v146, v146
	v_mul_f32_e32 v147, 0xbfb8aa3b, v86
	v_log_f32_e32 v144, v144
	v_log_f32_e32 v145, v145
	v_exp_f32_e32 v147, v147
	v_add_f32_e32 v146, 1.0, v146
	v_rcp_f32_e32 v146, v146
	v_pk_mul_f32 v[144:145], v[144:145], s[40:41] op_sel_hi:[1,0]
	v_add_f32_e32 v147, 1.0, v147
	v_rcp_f32_e32 v147, v147
; __device__ __forceinline__ float sigmoidf_(float a) { return __builtin_amdgcn_rcpf(1.f + __expf(-a)); }
;   __device__ __forceinline__ void operator()(const Acc& acc, int brow, int bcol, int wr, int wc, int fr, int fq, int nai) const {
;     ...
;         for (int ai = 0; ai < 2; ++ai)
; #pragma unroll
;           for (int m = 0; m < 4; ++m) if (ai < nai) {
;             const int r = brow + 128 * ai + 64 * wr + 16 * m + fr;
;             h16x8 hv;
; #pragma unroll
;             for (int n = 0; n < 2; ++n) {
;               const f32x4 v = acc[ai][bj][m][n];
; #pragma unroll
;               for (int j = 0; j < 4; ++j) hv[4 * n + j] = (_Float16)(0.6931471805599453f * __builtin_amdgcn_logf(lb[n][j] + (1.f - lb[n][j]) * sigmoidf_(v[j])));
;             }
;             *(h16x8*)(O + (size_t)r * DM + c) = hv;
	v_cvt_pk_f16_f32 v148, v144, v145
	v_fma_f32 v144, v146, v182, v64
	v_mul_f32_e32 v146, 0xbfb8aa3b, v87
	v_exp_f32_e32 v146, v146
	v_fma_f32 v145, v147, v179, v156
	v_log_f32_e32 v144, v144
	v_log_f32_e32 v145, v145
	v_add_f32_e32 v146, 1.0, v146
	v_rcp_f32_e32 v146, v146
	v_mul_f32_e32 v147, 0xbfb8aa3b, v80
	v_exp_f32_e32 v147, v147
	v_pk_mul_f32 v[144:145], v[144:145], s[40:41] op_sel_hi:[1,0]
	v_fma_f32 v146, v146, v183, v172
	v_cvt_pk_f16_f32 v145, v144, v145
	v_alignbit_b32 v143, v148, v143, 16
	v_alignbit_b32 v144, v145, v148, 16
	v_log_f32_e32 v148, v146
	v_add_f32_e32 v146, 1.0, v147
	v_mul_f32_e32 v147, 0xbfb8aa3b, v81
	v_exp_f32_e32 v147, v147
	v_rcp_f32_e32 v146, v146
	v_add_f32_e32 v149, 1.0, v149
	v_rcp_f32_e32 v149, v149
	v_add_f32_e32 v147, 1.0, v147
	v_rcp_f32_e32 v147, v147
	v_fma_f32 v146, v146, v175, v173
	v_log_f32_e32 v150, v146
	v_lshrrev_b32_e32 v145, 16, v145
	v_fma_f32 v146, v147, v180, v170
	v_fma_f32 v147, v149, v174, v171
	v_log_f32_e32 v146, v146
	v_log_f32_e32 v147, v147
	v_fma_mixhi_f16 v145, v148, s40, 0
	global_store_dwordx4 v[152:153], v[142:145], off offset:256
	s_nop 1
	v_mul_f32_e32 v145, 0xbfb8aa3b, v83
	v_pk_mul_f32 v[142:143], v[146:147], s[40:41] op_sel_hi:[1,0]
	v_exp_f32_e32 v145, v145
	v_mul_f32_e32 v146, 0xbfb8aa3b, v76
	v_exp_f32_e32 v146, v146
	v_cvt_pk_f16_f32 v143, v142, v143
	v_add_f32_e32 v142, 1.0, v145
	v_rcp_f32_e32 v145, v142
	v_add_f32_e32 v142, 1.0, v146
	v_rcp_f32_e32 v146, v142
	v_fma_mixlo_f16 v144, v150, s40, 0
	v_pack_b32_f16 v142, v144, v143
	v_fma_f32 v144, v145, v181, v157
	v_fma_f32 v145, v146, v177, v169
	v_mul_f32_e32 v146, 0xbfb8aa3b, v77
	v_mul_f32_e32 v147, 0xbfb8aa3b, v78
	v_exp_f32_e32 v146, v146
	v_exp_f32_e32 v147, v147
	v_log_f32_e32 v144, v144
	v_log_f32_e32 v145, v145
	v_add_f32_e32 v146, 1.0, v146
	v_add_f32_e32 v147, 1.0, v147
	v_rcp_f32_e32 v146, v146
	v_rcp_f32_e32 v147, v147
	v_pk_mul_f32 v[144:145], v[144:145], s[40:41] op_sel_hi:[1,0]
	s_nop 0
	v_cvt_pk_f16_f32 v148, v144, v145
	v_fma_f32 v144, v146, v182, v64
	v_fma_f32 v145, v147, v179, v156
	v_log_f32_e32 v144, v144
	v_log_f32_e32 v145, v145
	v_mul_f32_e32 v146, 0xbfb8aa3b, v79
	v_exp_f32_e32 v146, v146
	v_mul_f32_e32 v147, 0xbfb8aa3b, v72
	v_exp_f32_e32 v147, v147
	v_pk_mul_f32 v[144:145], v[144:145], s[40:41] op_sel_hi:[1,0]
	v_add_f32_e32 v146, 1.0, v146
	v_cvt_pk_f16_f32 v145, v144, v145
	v_alignbit_b32 v143, v148, v143, 16
	v_alignbit_b32 v144, v145, v148, 16
	v_rcp_f32_e32 v146, v146
	v_add_f32_e32 v147, 1.0, v147
	v_mul_f32_e32 v148, 0xbfb8aa3b, v73
	v_rcp_f32_e32 v147, v147
	v_exp_f32_e32 v148, v148
	v_fma_f32 v146, v146, v183, v172
	v_log_f32_e32 v146, v146
	v_fmac_f32_e32 v173, v147, v175
	v_add_f32_e32 v147, 1.0, v148
	v_mul_f32_e32 v148, 0xbfb8aa3b, v74
	v_exp_f32_e32 v148, v148
	v_lshrrev_b32_e32 v145, 16, v145
	v_fma_mixhi_f16 v145, v146, s40, 0
	global_store_dwordx4 v[154:155], v[142:145], off offset:256
	v_rcp_f32_e32 v147, v147
	v_log_f32_e32 v146, v173
	v_add_f32_e32 v142, 1.0, v148
	v_rcp_f32_e32 v143, v142
	v_mul_f32_e32 v142, 0xbfb8aa3b, v75
	v_exp_f32_e32 v144, v142
	v_fmac_f32_e32 v170, v147, v180
	v_fmac_f32_e32 v171, v143, v174
	v_log_f32_e32 v142, v170
	v_log_f32_e32 v143, v171
	v_add_f32_e32 v144, 1.0, v144
	v_mul_f32_e32 v145, 0xbfb8aa3b, v68
	v_rcp_f32_e32 v144, v144
	v_exp_f32_e32 v145, v145
	v_pk_mul_f32 v[142:143], v[142:143], s[40:41] op_sel_hi:[1,0]
	v_fma_mixlo_f16 v146, v146, s40, 0
	v_cvt_pk_f16_f32 v143, v142, v143
	v_fmac_f32_e32 v157, v144, v181
	v_add_f32_e32 v142, 1.0, v145
	v_mul_f32_e32 v144, 0xbfb8aa3b, v69
	v_rcp_f32_e32 v142, v142
	v_exp_f32_e32 v147, v144
	v_log_f32_e32 v144, v157
	v_fmac_f32_e32 v169, v142, v177
	v_add_f32_e32 v142, 1.0, v147
	v_rcp_f32_e32 v147, v142
	v_mul_f32_e32 v142, 0xbfb8aa3b, v70
	v_exp_f32_e32 v148, v142
	v_pack_b32_f16 v142, v146, v143
	v_fmac_f32_e32 v64, v147, v182
	v_log_f32_e32 v145, v169
	v_add_f32_e32 v146, 1.0, v148
	v_rcp_f32_e32 v147, v146
	v_mul_f32_e32 v146, 0xbfb8aa3b, v71
	v_exp_f32_e32 v148, v146
	v_log_f32_e32 v146, v64
	v_fmac_f32_e32 v156, v147, v179
	v_log_f32_e32 v147, v156
	v_add_f32_e32 v64, 1.0, v148
	v_rcp_f32_e32 v64, v64
	v_pk_mul_f32 v[144:145], v[144:145], s[40:41] op_sel_hi:[1,0]
	v_fmac_f32_e32 v172, v64, v183
	v_log_f32_e32 v64, v172
	v_cvt_pk_f16_f32 v148, v144, v145
	v_pk_mul_f32 v[144:145], v[146:147], s[40:41] op_sel_hi:[1,0]
	v_alignbit_b32 v143, v148, v143, 16
	v_cvt_pk_f16_f32 v145, v144, v145
	v_alignbit_b32 v144, v145, v148, 16
	v_lshrrev_b32_e32 v145, 16, v145
	v_fma_mixhi_f16 v145, v64, s40, 0
	global_store_dwordx4 v[66:67], v[142:145], off offset:256
